# EpiResid epilogues (out-proj, MLP-down): the 16 residual-stream tile loads issued in two batches instead of 16 serialized round trips (on v87)
# baseline (speedup 1.0000x reference)
.LBB0_859:
	v_lshl_add_u32 v152, s16, 8, v142
	v_ashrrev_i32_e32 v153, 31, v152
	v_lshl_or_b32 v150, s6, 8, v143
	v_lshlrev_b64 v[154:155], 12, v[152:153]
	v_ashrrev_i32_e32 v151, 31, v150
	v_lshl_add_u64 v[154:155], s[80:81], 0, v[154:155]
	v_lshl_add_u64 v[154:155], v[150:151], 1, v[154:155]
	global_load_dwordx4 v[188:191], v[154:155], off
	global_load_dwordx4 v[192:195], v[154:155], off offset:256
	v_add_co_u32_e32 v184, vcc, 0x10000, v154
	v_addc_co_u32_e32 v185, vcc, 0, v155, vcc
	global_load_dwordx4 v[196:199], v[184:185], off
	global_load_dwordx4 v[214:217], v[184:185], off offset:256
	v_add_co_u32_e32 v184, vcc, 0x20000, v154
	v_addc_co_u32_e32 v185, vcc, 0, v155, vcc
	global_load_dwordx4 v[218:221], v[184:185], off
	global_load_dwordx4 v[222:225], v[184:185], off offset:256
	v_add_co_u32_e32 v184, vcc, 0x30000, v154
	v_addc_co_u32_e32 v185, vcc, 0, v155, vcc
	global_load_dwordx4 v[226:229], v[184:185], off
	global_load_dwordx4 v[230:233], v[184:185], off offset:256
	v_add_co_u32_e32 v184, vcc, 0x80000, v154
	v_addc_co_u32_e32 v185, vcc, 0, v155, vcc
	global_load_dwordx4 v[234:237], v[184:185], off
	global_load_dwordx4 v[238:241], v[184:185], off offset:256
	v_add_co_u32_e32 v184, vcc, 0x90000, v154
	v_addc_co_u32_e32 v185, vcc, 0, v155, vcc
	global_load_dwordx4 v[242:245], v[184:185], off
	global_load_dwordx4 v[246:249], v[184:185], off offset:256
	s_waitcnt vmcnt(0)
	v_mov_b32_e32 v158, v188
	v_mov_b32_e32 v159, v189
	v_mov_b32_e32 v160, v190
	v_mov_b32_e32 v161, v191
	v_lshlrev_b32_e32 v162, 16, v158
	v_and_b32_e32 v163, 0xffff0000, v158
	v_lshlrev_b32_e32 v158, 16, v159
	v_and_b32_e32 v159, 0xffff0000, v159
	v_pk_add_f32 v[172:173], v[134:135], v[158:159]
	v_pk_add_f32 v[158:159], v[132:133], v[162:163]
	v_lshlrev_b32_e32 v170, 16, v160
	v_and_b32_e32 v171, 0xffff0000, v160
	v_lshlrev_b32_e32 v160, 16, v161
	v_and_b32_e32 v161, 0xffff0000, v161
	v_mul_f32_e32 v157, v159, v159
	v_mul_f32_e32 v167, v173, v173
	v_pk_add_f32 v[162:163], v[130:131], v[160:161]
	v_pk_add_f32 v[160:161], v[128:129], v[170:171]
	v_fmac_f32_e32 v157, v158, v158
	v_fmac_f32_e32 v167, v172, v172
	v_add_f32_e32 v157, v157, v167
	v_mul_f32_e32 v167, v161, v161
	v_fmac_f32_e32 v167, v160, v160
	v_cvt_pk_bf16_f32 v158, v158, v159
	v_cvt_pk_bf16_f32 v159, v172, v173
	v_cvt_pk_bf16_f32 v160, v160, v161
	v_cvt_pk_bf16_f32 v161, v162, v163
	global_store_dwordx4 v[154:155], v[158:161], off
	s_nop 1
	v_mov_b32_e32 v158, v192
	v_mov_b32_e32 v159, v193
	v_mov_b32_e32 v160, v194
	v_mov_b32_e32 v161, v195
	v_add_f32_e32 v157, v167, v157
	v_mul_f32_e32 v167, v163, v163
	v_fmac_f32_e32 v167, v162, v162
	v_add_f32_e32 v157, v167, v157
	v_lshlrev_b32_e32 v162, 16, v158
	v_and_b32_e32 v163, 0xffff0000, v158
	v_lshlrev_b32_e32 v158, 16, v159
	v_and_b32_e32 v159, 0xffff0000, v159
	v_pk_add_f32 v[172:173], v[118:119], v[158:159]
	v_pk_add_f32 v[158:159], v[116:117], v[162:163]
	v_lshlrev_b32_e32 v170, 16, v160
	v_and_b32_e32 v171, 0xffff0000, v160
	v_lshlrev_b32_e32 v160, 16, v161
	v_and_b32_e32 v161, 0xffff0000, v161
	v_mul_f32_e32 v167, v159, v159
	v_mul_f32_e32 v169, v173, v173
	v_pk_add_f32 v[162:163], v[104:105], v[160:161]
	v_pk_add_f32 v[160:161], v[102:103], v[170:171]
	v_fmac_f32_e32 v167, v158, v158
	v_fmac_f32_e32 v169, v172, v172
	v_add_f32_e32 v167, v167, v169
	v_mul_f32_e32 v169, v161, v161
	v_fmac_f32_e32 v169, v160, v160
	v_cvt_pk_bf16_f32 v158, v158, v159
	v_cvt_pk_bf16_f32 v159, v172, v173
	v_cvt_pk_bf16_f32 v160, v160, v161
	v_cvt_pk_bf16_f32 v161, v162, v163
	global_store_dwordx4 v[154:155], v[158:161], off offset:256
	v_and_b32_e32 v155, 64, v210
	v_add_f32_e32 v167, v169, v167
	v_mul_f32_e32 v169, v163, v163
	v_xor_b32_e32 v154, 16, v210
	v_add_u32_e32 v155, 64, v155
	v_fmac_f32_e32 v169, v162, v162
	v_cmp_lt_i32_e32 vcc, v154, v155
	v_add_f32_e32 v167, v169, v167
	v_add_f32_e32 v167, v157, v167
	v_cndmask_b32_e32 v154, v210, v154, vcc
	v_lshlrev_b32_e32 v157, 2, v154
	ds_bpermute_b32 v154, v157, v167
	v_xor_b32_e32 v158, 32, v210
	v_cmp_lt_i32_e32 vcc, v158, v155
	s_waitcnt lgkmcnt(0)
	v_add_f32_e32 v154, v167, v154
	v_cndmask_b32_e32 v155, v210, v158, vcc
	v_lshlrev_b32_e32 v158, 2, v155
	ds_bpermute_b32 v155, v158, v154
	s_and_saveexec_b64 s[8:9], s[38:39]
	s_cbranch_execz .LBB0_861
	s_waitcnt lgkmcnt(0)
	v_add_f32_e32 v159, v154, v155
	s_lshl_b32 s66, s6, 2
	v_lshlrev_b64 v[154:155], 7, v[152:153]
	s_ashr_i32 s67, s66, 31
	v_lshl_add_u64 v[154:155], s[4:5], 0, v[154:155]
	v_lshl_add_u64 v[154:155], s[66:67], 2, v[154:155]
	s_lshl_b32 s88, s60, 2
	v_lshl_add_u64 v[154:155], v[154:155], 0, s[88:89]
	global_store_dword v[154:155], v159, off
.LBB0_861:
	s_or_b64 exec, exec, s[8:9]
	v_or_b32_e32 v154, 16, v152
	s_waitcnt lgkmcnt(0)
	v_ashrrev_i32_e32 v155, 31, v154
	v_lshlrev_b64 v[160:161], 12, v[154:155]
	v_lshl_add_u64 v[160:161], s[80:81], 0, v[160:161]
	v_lshl_add_u64 v[170:171], v[150:151], 1, v[160:161]
	v_mov_b32_e32 v160, v196
	v_mov_b32_e32 v161, v197
	v_mov_b32_e32 v162, v198
	v_mov_b32_e32 v163, v199
	v_lshlrev_b32_e32 v172, 16, v160
	v_and_b32_e32 v173, 0xffff0000, v160
	v_lshlrev_b32_e32 v160, 16, v161
	v_and_b32_e32 v161, 0xffff0000, v161
	v_pk_add_f32 v[186:187], v[126:127], v[160:161]
	v_pk_add_f32 v[160:161], v[124:125], v[172:173]
	v_lshlrev_b32_e32 v184, 16, v162
	v_and_b32_e32 v185, 0xffff0000, v162
	v_lshlrev_b32_e32 v162, 16, v163
	v_and_b32_e32 v163, 0xffff0000, v163
	v_mul_f32_e32 v153, v161, v161
	v_mul_f32_e32 v159, v187, v187
	v_pk_add_f32 v[172:173], v[122:123], v[162:163]
	v_pk_add_f32 v[162:163], v[120:121], v[184:185]
	v_fmac_f32_e32 v153, v160, v160
	v_fmac_f32_e32 v159, v186, v186
	v_add_f32_e32 v153, v153, v159
	v_mul_f32_e32 v159, v163, v163
	v_fmac_f32_e32 v159, v162, v162
	v_cvt_pk_bf16_f32 v160, v160, v161
	v_cvt_pk_bf16_f32 v161, v186, v187
	v_cvt_pk_bf16_f32 v162, v162, v163
	v_cvt_pk_bf16_f32 v163, v172, v173
	global_store_dwordx4 v[170:171], v[160:163], off
	s_nop 1
	v_mov_b32_e32 v160, v214
	v_mov_b32_e32 v161, v215
	v_mov_b32_e32 v162, v216
	v_mov_b32_e32 v163, v217
	v_add_co_u32_e32 v184, vcc, 0x90000, v170
	v_addc_co_u32_e32 v185, vcc, 0, v171, vcc
	global_load_dwordx4 v[188:191], v[184:185], off
	global_load_dwordx4 v[192:195], v[184:185], off offset:256
	v_add_co_u32_e32 v184, vcc, 0xa0000, v170
	v_addc_co_u32_e32 v185, vcc, 0, v171, vcc
	global_load_dwordx4 v[196:199], v[184:185], off
	global_load_dwordx4 v[214:217], v[184:185], off offset:256
	v_add_f32_e32 v153, v159, v153
	v_mul_f32_e32 v159, v173, v173
	v_fmac_f32_e32 v159, v172, v172
	v_add_f32_e32 v153, v159, v153
	v_lshlrev_b32_e32 v172, 16, v160
	v_and_b32_e32 v173, 0xffff0000, v160
	v_lshlrev_b32_e32 v160, 16, v161
	v_and_b32_e32 v161, 0xffff0000, v161
	v_pk_add_f32 v[186:187], v[96:97], v[160:161]
	v_pk_add_f32 v[160:161], v[94:95], v[172:173]
	v_lshlrev_b32_e32 v184, 16, v162
	v_and_b32_e32 v185, 0xffff0000, v162
	v_lshlrev_b32_e32 v162, 16, v163
	v_and_b32_e32 v163, 0xffff0000, v163
	v_mul_f32_e32 v159, v161, v161
	v_mul_f32_e32 v167, v187, v187
	v_pk_add_f32 v[172:173], v[88:89], v[162:163]
	v_pk_add_f32 v[162:163], v[86:87], v[184:185]
	v_fmac_f32_e32 v159, v160, v160
	v_fmac_f32_e32 v167, v186, v186
	v_add_f32_e32 v159, v159, v167
	v_mul_f32_e32 v167, v163, v163
	v_fmac_f32_e32 v167, v162, v162
	v_add_f32_e32 v159, v167, v159
	v_mul_f32_e32 v167, v173, v173
	v_fmac_f32_e32 v167, v172, v172
	v_add_f32_e32 v159, v167, v159
	v_add_f32_e32 v153, v153, v159
	ds_bpermute_b32 v159, v157, v153
	v_cvt_pk_bf16_f32 v160, v160, v161
	v_cvt_pk_bf16_f32 v161, v186, v187
	v_cvt_pk_bf16_f32 v162, v162, v163
	v_cvt_pk_bf16_f32 v163, v172, v173
	s_waitcnt lgkmcnt(0)
	v_add_f32_e32 v153, v153, v159
	ds_bpermute_b32 v159, v158, v153
	global_store_dwordx4 v[170:171], v[160:163], off offset:256
	s_and_saveexec_b64 s[8:9], s[38:39]
	s_cbranch_execz .LBB0_863
	s_lshl_b32 s66, s6, 2
	v_lshlrev_b64 v[154:155], 7, v[154:155]
	s_ashr_i32 s67, s66, 31
	v_lshl_add_u64 v[154:155], s[4:5], 0, v[154:155]
	v_lshl_add_u64 v[154:155], s[66:67], 2, v[154:155]
	s_lshl_b32 s88, s60, 2
	s_waitcnt lgkmcnt(0)
	v_add_f32_e32 v153, v153, v159
	v_lshl_add_u64 v[154:155], v[154:155], 0, s[88:89]
	global_store_dword v[154:155], v153, off
.LBB0_863:
	s_or_b64 exec, exec, s[8:9]
	v_or_b32_e32 v154, 32, v152
	v_ashrrev_i32_e32 v155, 31, v154
	v_lshlrev_b64 v[160:161], 12, v[154:155]
	v_lshl_add_u64 v[160:161], s[80:81], 0, v[160:161]
	v_lshl_add_u64 v[170:171], v[150:151], 1, v[160:161]
	v_mov_b32_e32 v160, v218
	v_mov_b32_e32 v161, v219
	v_mov_b32_e32 v162, v220
	v_mov_b32_e32 v163, v221
	v_lshlrev_b32_e32 v172, 16, v160
	v_and_b32_e32 v173, 0xffff0000, v160
	v_lshlrev_b32_e32 v160, 16, v161
	v_and_b32_e32 v161, 0xffff0000, v161
	v_pk_add_f32 v[186:187], v[108:109], v[160:161]
	v_pk_add_f32 v[160:161], v[106:107], v[172:173]
	v_lshlrev_b32_e32 v184, 16, v162
	v_and_b32_e32 v185, 0xffff0000, v162
	v_lshlrev_b32_e32 v162, 16, v163
	v_and_b32_e32 v163, 0xffff0000, v163
	v_mul_f32_e32 v153, v161, v161
	s_waitcnt lgkmcnt(0)
	v_mul_f32_e32 v159, v187, v187
	v_pk_add_f32 v[172:173], v[100:101], v[162:163]
	v_pk_add_f32 v[162:163], v[98:99], v[184:185]
	v_fmac_f32_e32 v153, v160, v160
	v_fmac_f32_e32 v159, v186, v186
	v_add_f32_e32 v153, v153, v159
	v_mul_f32_e32 v159, v163, v163
	v_fmac_f32_e32 v159, v162, v162
	v_cvt_pk_bf16_f32 v160, v160, v161
	v_cvt_pk_bf16_f32 v161, v186, v187
	v_cvt_pk_bf16_f32 v162, v162, v163
	v_cvt_pk_bf16_f32 v163, v172, v173
	global_store_dwordx4 v[170:171], v[160:163], off
	s_nop 1
	v_mov_b32_e32 v160, v222
	v_mov_b32_e32 v161, v223
	v_mov_b32_e32 v162, v224
	v_mov_b32_e32 v163, v225
	v_add_f32_e32 v153, v159, v153
	v_mul_f32_e32 v159, v173, v173
	v_fmac_f32_e32 v159, v172, v172
	v_add_f32_e32 v153, v159, v153
	v_lshlrev_b32_e32 v172, 16, v160
	v_and_b32_e32 v173, 0xffff0000, v160
	v_lshlrev_b32_e32 v160, 16, v161
	v_and_b32_e32 v161, 0xffff0000, v161
	v_pk_add_f32 v[186:187], v[80:81], v[160:161]
	v_pk_add_f32 v[160:161], v[78:79], v[172:173]
	v_lshlrev_b32_e32 v184, 16, v162
	v_and_b32_e32 v185, 0xffff0000, v162
	v_lshlrev_b32_e32 v162, 16, v163
	v_and_b32_e32 v163, 0xffff0000, v163
	v_mul_f32_e32 v159, v161, v161
	v_mul_f32_e32 v167, v187, v187
	v_pk_add_f32 v[172:173], v[76:77], v[162:163]
	v_pk_add_f32 v[162:163], v[74:75], v[184:185]
	v_fmac_f32_e32 v159, v160, v160
	v_fmac_f32_e32 v167, v186, v186
	v_add_f32_e32 v159, v159, v167
	v_mul_f32_e32 v167, v163, v163
	v_fmac_f32_e32 v167, v162, v162
	v_add_f32_e32 v159, v167, v159
	v_mul_f32_e32 v167, v173, v173
	v_fmac_f32_e32 v167, v172, v172
	v_add_f32_e32 v159, v167, v159
	v_add_f32_e32 v153, v153, v159
	ds_bpermute_b32 v159, v157, v153
	v_cvt_pk_bf16_f32 v160, v160, v161
	v_cvt_pk_bf16_f32 v161, v186, v187
	v_cvt_pk_bf16_f32 v162, v162, v163
	v_cvt_pk_bf16_f32 v163, v172, v173
	s_waitcnt lgkmcnt(0)
	v_add_f32_e32 v153, v153, v159
	ds_bpermute_b32 v159, v158, v153
	global_store_dwordx4 v[170:171], v[160:163], off offset:256
	s_and_saveexec_b64 s[8:9], s[38:39]
	s_cbranch_execz .LBB0_865
	s_lshl_b32 s66, s6, 2
	v_lshlrev_b64 v[154:155], 7, v[154:155]
	s_ashr_i32 s67, s66, 31
	v_lshl_add_u64 v[154:155], s[4:5], 0, v[154:155]
	v_lshl_add_u64 v[154:155], s[66:67], 2, v[154:155]
	s_lshl_b32 s88, s60, 2
	s_waitcnt lgkmcnt(0)
	v_add_f32_e32 v153, v153, v159
	v_lshl_add_u64 v[154:155], v[154:155], 0, s[88:89]
	global_store_dword v[154:155], v153, off
.LBB0_865:
	s_or_b64 exec, exec, s[8:9]
	v_or_b32_e32 v154, 48, v152
	v_ashrrev_i32_e32 v155, 31, v154
	v_lshlrev_b64 v[160:161], 12, v[154:155]
	v_lshl_add_u64 v[160:161], s[80:81], 0, v[160:161]
	v_lshl_add_u64 v[170:171], v[150:151], 1, v[160:161]
	v_mov_b32_e32 v160, v226
	v_mov_b32_e32 v161, v227
	v_mov_b32_e32 v162, v228
	v_mov_b32_e32 v163, v229
	v_lshlrev_b32_e32 v172, 16, v160
	v_and_b32_e32 v173, 0xffff0000, v160
	v_lshlrev_b32_e32 v160, 16, v161
	v_and_b32_e32 v161, 0xffff0000, v161
	v_pk_add_f32 v[186:187], v[92:93], v[160:161]
	v_pk_add_f32 v[160:161], v[90:91], v[172:173]
	v_lshlrev_b32_e32 v184, 16, v162
	v_and_b32_e32 v185, 0xffff0000, v162
	v_lshlrev_b32_e32 v162, 16, v163
	v_and_b32_e32 v163, 0xffff0000, v163
	v_mul_f32_e32 v153, v161, v161
	s_waitcnt lgkmcnt(0)
	v_mul_f32_e32 v159, v187, v187
	v_pk_add_f32 v[172:173], v[84:85], v[162:163]
	v_pk_add_f32 v[162:163], v[82:83], v[184:185]
	v_fmac_f32_e32 v153, v160, v160
	v_fmac_f32_e32 v159, v186, v186
	v_add_f32_e32 v153, v153, v159
	v_mul_f32_e32 v159, v163, v163
	v_fmac_f32_e32 v159, v162, v162
	v_cvt_pk_bf16_f32 v160, v160, v161
	v_cvt_pk_bf16_f32 v161, v186, v187
	v_cvt_pk_bf16_f32 v162, v162, v163
	v_cvt_pk_bf16_f32 v163, v172, v173
	global_store_dwordx4 v[170:171], v[160:163], off
	s_nop 1
	v_mov_b32_e32 v160, v230
	v_mov_b32_e32 v161, v231
	v_mov_b32_e32 v162, v232
	v_mov_b32_e32 v163, v233
	v_add_f32_e32 v153, v159, v153
	v_mul_f32_e32 v159, v173, v173
	v_fmac_f32_e32 v159, v172, v172
	v_add_f32_e32 v153, v159, v153
	v_lshlrev_b32_e32 v172, 16, v160
	v_and_b32_e32 v173, 0xffff0000, v160
	v_lshlrev_b32_e32 v160, 16, v161
	v_and_b32_e32 v161, 0xffff0000, v161
	v_pk_add_f32 v[186:187], v[72:73], v[160:161]
	v_pk_add_f32 v[160:161], v[70:71], v[172:173]
	v_lshlrev_b32_e32 v184, 16, v162
	v_and_b32_e32 v185, 0xffff0000, v162
	v_lshlrev_b32_e32 v162, 16, v163
	v_and_b32_e32 v163, 0xffff0000, v163
	v_mul_f32_e32 v159, v161, v161
	v_mul_f32_e32 v167, v187, v187
	v_pk_add_f32 v[172:173], v[68:69], v[162:163]
	v_pk_add_f32 v[162:163], v[66:67], v[184:185]
	v_fmac_f32_e32 v159, v160, v160
	v_fmac_f32_e32 v167, v186, v186
	v_add_f32_e32 v159, v159, v167
	v_mul_f32_e32 v167, v163, v163
	v_fmac_f32_e32 v167, v162, v162
	v_add_f32_e32 v159, v167, v159
	v_mul_f32_e32 v167, v173, v173
	v_fmac_f32_e32 v167, v172, v172
	v_add_f32_e32 v159, v167, v159
	v_add_f32_e32 v153, v153, v159
	ds_bpermute_b32 v159, v157, v153
	v_cvt_pk_bf16_f32 v160, v160, v161
	v_cvt_pk_bf16_f32 v161, v186, v187
	v_cvt_pk_bf16_f32 v162, v162, v163
	v_cvt_pk_bf16_f32 v163, v172, v173
	s_waitcnt lgkmcnt(0)
	v_add_f32_e32 v153, v153, v159
	ds_bpermute_b32 v159, v158, v153
	global_store_dwordx4 v[170:171], v[160:163], off offset:256
	s_and_saveexec_b64 s[8:9], s[38:39]
	s_cbranch_execz .LBB0_867
	s_lshl_b32 s66, s6, 2
	v_lshlrev_b64 v[154:155], 7, v[154:155]
	s_ashr_i32 s67, s66, 31
	v_lshl_add_u64 v[154:155], s[4:5], 0, v[154:155]
	v_lshl_add_u64 v[154:155], s[66:67], 2, v[154:155]
	s_lshl_b32 s88, s60, 2
	s_waitcnt lgkmcnt(0)
	v_add_f32_e32 v153, v153, v159
	v_lshl_add_u64 v[154:155], v[154:155], 0, s[88:89]
	global_store_dword v[154:155], v153, off
.LBB0_867:
	s_or_b64 exec, exec, s[8:9]
	v_add_u32_e32 v154, 0x80, v152
	v_ashrrev_i32_e32 v155, 31, v154
	v_lshlrev_b64 v[160:161], 12, v[154:155]
	v_lshl_add_u64 v[160:161], s[80:81], 0, v[160:161]
	v_lshl_add_u64 v[170:171], v[150:151], 1, v[160:161]
	v_mov_b32_e32 v160, v234
	v_mov_b32_e32 v161, v235
	v_mov_b32_e32 v162, v236
	v_mov_b32_e32 v163, v237
	v_lshlrev_b32_e32 v172, 16, v160
	v_and_b32_e32 v173, 0xffff0000, v160
	v_lshlrev_b32_e32 v160, 16, v161
	v_and_b32_e32 v161, 0xffff0000, v161
	v_pk_add_f32 v[186:187], v[64:65], v[160:161]
	v_pk_add_f32 v[160:161], v[62:63], v[172:173]
	v_lshlrev_b32_e32 v184, 16, v162
	v_and_b32_e32 v185, 0xffff0000, v162
	v_lshlrev_b32_e32 v162, 16, v163
	v_and_b32_e32 v163, 0xffff0000, v163
	v_mul_f32_e32 v153, v161, v161
	s_waitcnt lgkmcnt(0)
	v_mul_f32_e32 v159, v187, v187
	v_pk_add_f32 v[172:173], v[60:61], v[162:163]
	v_pk_add_f32 v[162:163], v[58:59], v[184:185]
	v_fmac_f32_e32 v153, v160, v160
	v_fmac_f32_e32 v159, v186, v186
	v_add_f32_e32 v153, v153, v159
	v_mul_f32_e32 v159, v163, v163
	v_fmac_f32_e32 v159, v162, v162
	v_cvt_pk_bf16_f32 v160, v160, v161
	v_cvt_pk_bf16_f32 v161, v186, v187
	v_cvt_pk_bf16_f32 v162, v162, v163
	v_cvt_pk_bf16_f32 v163, v172, v173
	global_store_dwordx4 v[170:171], v[160:163], off
	s_nop 1
	v_mov_b32_e32 v160, v238
	v_mov_b32_e32 v161, v239
	v_mov_b32_e32 v162, v240
	v_mov_b32_e32 v163, v241
	v_add_f32_e32 v153, v159, v153
	v_mul_f32_e32 v159, v173, v173
	v_fmac_f32_e32 v159, v172, v172
	v_add_f32_e32 v153, v159, v153
	v_lshlrev_b32_e32 v172, 16, v160
	v_and_b32_e32 v173, 0xffff0000, v160
	v_lshlrev_b32_e32 v160, 16, v161
	v_and_b32_e32 v161, 0xffff0000, v161
	v_pk_add_f32 v[186:187], v[48:49], v[160:161]
	v_pk_add_f32 v[160:161], v[46:47], v[172:173]
	v_lshlrev_b32_e32 v184, 16, v162
	v_and_b32_e32 v185, 0xffff0000, v162
	v_lshlrev_b32_e32 v162, 16, v163
	v_and_b32_e32 v163, 0xffff0000, v163
	v_mul_f32_e32 v159, v161, v161
	v_mul_f32_e32 v167, v187, v187
	v_pk_add_f32 v[172:173], v[40:41], v[162:163]
	v_pk_add_f32 v[162:163], v[38:39], v[184:185]
	v_fmac_f32_e32 v159, v160, v160
	v_fmac_f32_e32 v167, v186, v186
	v_add_f32_e32 v159, v159, v167
	v_mul_f32_e32 v167, v163, v163
	v_fmac_f32_e32 v167, v162, v162
	v_add_f32_e32 v159, v167, v159
	v_mul_f32_e32 v167, v173, v173
	v_fmac_f32_e32 v167, v172, v172
	v_add_f32_e32 v159, v167, v159
	v_add_f32_e32 v153, v153, v159
	ds_bpermute_b32 v159, v157, v153
	v_cvt_pk_bf16_f32 v160, v160, v161
	v_cvt_pk_bf16_f32 v161, v186, v187
	v_cvt_pk_bf16_f32 v162, v162, v163
	v_cvt_pk_bf16_f32 v163, v172, v173
	s_waitcnt lgkmcnt(0)
	v_add_f32_e32 v153, v153, v159
	ds_bpermute_b32 v159, v158, v153
	global_store_dwordx4 v[170:171], v[160:163], off offset:256
	s_and_saveexec_b64 s[8:9], s[38:39]
	s_cbranch_execz .LBB0_869
	s_lshl_b32 s66, s6, 2
	v_lshlrev_b64 v[154:155], 7, v[154:155]
	s_ashr_i32 s67, s66, 31
	v_lshl_add_u64 v[154:155], s[4:5], 0, v[154:155]
	v_lshl_add_u64 v[154:155], s[66:67], 2, v[154:155]
	s_lshl_b32 s88, s60, 2
	s_waitcnt lgkmcnt(0)
	v_add_f32_e32 v153, v153, v159
	v_lshl_add_u64 v[154:155], v[154:155], 0, s[88:89]
	global_store_dword v[154:155], v153, off
.LBB0_869:
	s_or_b64 exec, exec, s[8:9]
	v_add_u32_e32 v154, 0x90, v152
	v_ashrrev_i32_e32 v155, 31, v154
	v_lshlrev_b64 v[160:161], 12, v[154:155]
	v_lshl_add_u64 v[160:161], s[80:81], 0, v[160:161]
	v_lshl_add_u64 v[170:171], v[150:151], 1, v[160:161]
	v_mov_b32_e32 v160, v242
	v_mov_b32_e32 v161, v243
	v_mov_b32_e32 v162, v244
	v_mov_b32_e32 v163, v245
	v_lshlrev_b32_e32 v172, 16, v160
	v_and_b32_e32 v173, 0xffff0000, v160
	v_lshlrev_b32_e32 v160, 16, v161
	v_and_b32_e32 v161, 0xffff0000, v161
	v_pk_add_f32 v[186:187], v[56:57], v[160:161]
	v_pk_add_f32 v[160:161], v[54:55], v[172:173]
	v_lshlrev_b32_e32 v184, 16, v162
	v_and_b32_e32 v185, 0xffff0000, v162
	v_lshlrev_b32_e32 v162, 16, v163
	v_and_b32_e32 v163, 0xffff0000, v163
	v_mul_f32_e32 v153, v161, v161
	s_waitcnt lgkmcnt(0)
	v_mul_f32_e32 v159, v187, v187
	v_pk_add_f32 v[172:173], v[52:53], v[162:163]
	v_pk_add_f32 v[162:163], v[50:51], v[184:185]
	v_fmac_f32_e32 v153, v160, v160
	v_fmac_f32_e32 v159, v186, v186
	v_add_f32_e32 v153, v153, v159
	v_mul_f32_e32 v159, v163, v163
	v_fmac_f32_e32 v159, v162, v162
	v_cvt_pk_bf16_f32 v160, v160, v161
	v_cvt_pk_bf16_f32 v161, v186, v187
	v_cvt_pk_bf16_f32 v162, v162, v163
	v_cvt_pk_bf16_f32 v163, v172, v173
	global_store_dwordx4 v[170:171], v[160:163], off
	s_nop 1
	v_mov_b32_e32 v160, v246
	v_mov_b32_e32 v161, v247
	v_mov_b32_e32 v162, v248
	v_mov_b32_e32 v163, v249
	v_add_f32_e32 v153, v159, v153
	v_mul_f32_e32 v159, v173, v173
	v_fmac_f32_e32 v159, v172, v172
	v_add_f32_e32 v153, v159, v153
	v_lshlrev_b32_e32 v172, 16, v160
	v_and_b32_e32 v173, 0xffff0000, v160
	v_lshlrev_b32_e32 v160, 16, v161
	v_and_b32_e32 v161, 0xffff0000, v161
	v_pk_add_f32 v[186:187], v[32:33], v[160:161]
	v_pk_add_f32 v[160:161], v[30:31], v[172:173]
	v_lshlrev_b32_e32 v184, 16, v162
	v_and_b32_e32 v185, 0xffff0000, v162
	v_lshlrev_b32_e32 v162, 16, v163
	v_and_b32_e32 v163, 0xffff0000, v163
	v_mul_f32_e32 v159, v161, v161
	v_mul_f32_e32 v167, v187, v187
	v_pk_add_f32 v[172:173], v[24:25], v[162:163]
	v_pk_add_f32 v[162:163], v[22:23], v[184:185]
	v_fmac_f32_e32 v159, v160, v160
	v_fmac_f32_e32 v167, v186, v186
	v_add_f32_e32 v159, v159, v167
	v_mul_f32_e32 v167, v163, v163
	v_fmac_f32_e32 v167, v162, v162
	v_add_f32_e32 v159, v167, v159
	v_mul_f32_e32 v167, v173, v173
	v_fmac_f32_e32 v167, v172, v172
	v_add_f32_e32 v159, v167, v159
	v_add_f32_e32 v153, v153, v159
	ds_bpermute_b32 v159, v157, v153
	v_cvt_pk_bf16_f32 v160, v160, v161
	v_cvt_pk_bf16_f32 v161, v186, v187
	v_cvt_pk_bf16_f32 v162, v162, v163
	v_cvt_pk_bf16_f32 v163, v172, v173
	s_waitcnt lgkmcnt(0)
	v_add_f32_e32 v153, v153, v159
	ds_bpermute_b32 v159, v158, v153
	global_store_dwordx4 v[170:171], v[160:163], off offset:256
	s_and_saveexec_b64 s[8:9], s[38:39]
	s_cbranch_execz .LBB0_871
	s_lshl_b32 s66, s6, 2
	v_lshlrev_b64 v[154:155], 7, v[154:155]
	s_ashr_i32 s67, s66, 31
	v_lshl_add_u64 v[154:155], s[4:5], 0, v[154:155]
	v_lshl_add_u64 v[154:155], s[66:67], 2, v[154:155]
	s_lshl_b32 s88, s60, 2
	s_waitcnt lgkmcnt(0)
	v_add_f32_e32 v153, v153, v159
	v_lshl_add_u64 v[154:155], v[154:155], 0, s[88:89]
	global_store_dword v[154:155], v153, off
.LBB0_871:
	s_or_b64 exec, exec, s[8:9]
	v_add_u32_e32 v154, 0xa0, v152
	v_ashrrev_i32_e32 v155, 31, v154
	v_lshlrev_b64 v[160:161], 12, v[154:155]
	v_lshl_add_u64 v[160:161], s[80:81], 0, v[160:161]
	v_lshl_add_u64 v[170:171], v[150:151], 1, v[160:161]
	s_waitcnt vmcnt(6)
	v_mov_b32_e32 v160, v188
	v_mov_b32_e32 v161, v189
	v_mov_b32_e32 v162, v190
	v_mov_b32_e32 v163, v191
	v_lshlrev_b32_e32 v172, 16, v160
	v_and_b32_e32 v173, 0xffff0000, v160
	v_lshlrev_b32_e32 v160, 16, v161
	v_and_b32_e32 v161, 0xffff0000, v161
	v_pk_add_f32 v[186:187], v[44:45], v[160:161]
	v_pk_add_f32 v[160:161], v[42:43], v[172:173]
	v_lshlrev_b32_e32 v184, 16, v162
	v_and_b32_e32 v185, 0xffff0000, v162
	v_lshlrev_b32_e32 v162, 16, v163
	v_and_b32_e32 v163, 0xffff0000, v163
	v_mul_f32_e32 v153, v161, v161
	s_waitcnt lgkmcnt(0)
	v_mul_f32_e32 v159, v187, v187
	v_pk_add_f32 v[172:173], v[36:37], v[162:163]
	v_pk_add_f32 v[162:163], v[34:35], v[184:185]
	v_fmac_f32_e32 v153, v160, v160
	v_fmac_f32_e32 v159, v186, v186
	v_add_f32_e32 v153, v153, v159
	v_mul_f32_e32 v159, v163, v163
	v_fmac_f32_e32 v159, v162, v162
	v_cvt_pk_bf16_f32 v160, v160, v161
	v_cvt_pk_bf16_f32 v161, v186, v187
	v_cvt_pk_bf16_f32 v162, v162, v163
	v_cvt_pk_bf16_f32 v163, v172, v173
	global_store_dwordx4 v[170:171], v[160:163], off
	s_nop 1
	v_mov_b32_e32 v160, v192
	v_mov_b32_e32 v161, v193
	v_mov_b32_e32 v162, v194
	v_mov_b32_e32 v163, v195
	v_add_f32_e32 v153, v159, v153
	v_mul_f32_e32 v159, v173, v173
	v_fmac_f32_e32 v159, v172, v172
	v_add_f32_e32 v153, v159, v153
	v_lshlrev_b32_e32 v172, 16, v160
	v_and_b32_e32 v173, 0xffff0000, v160
	v_lshlrev_b32_e32 v160, 16, v161
	v_and_b32_e32 v161, 0xffff0000, v161
	v_pk_add_f32 v[186:187], v[16:17], v[160:161]
	v_pk_add_f32 v[160:161], v[14:15], v[172:173]
	v_lshlrev_b32_e32 v184, 16, v162
	v_and_b32_e32 v185, 0xffff0000, v162
	v_lshlrev_b32_e32 v162, 16, v163
	v_and_b32_e32 v163, 0xffff0000, v163
	v_mul_f32_e32 v159, v161, v161
	v_mul_f32_e32 v167, v187, v187
	v_pk_add_f32 v[172:173], v[12:13], v[162:163]
	v_pk_add_f32 v[162:163], v[10:11], v[184:185]
	v_fmac_f32_e32 v159, v160, v160
	v_fmac_f32_e32 v167, v186, v186
	v_add_f32_e32 v159, v159, v167
	v_mul_f32_e32 v167, v163, v163
	v_fmac_f32_e32 v167, v162, v162
	v_add_f32_e32 v159, v167, v159
	v_mul_f32_e32 v167, v173, v173
	v_fmac_f32_e32 v167, v172, v172
	v_add_f32_e32 v159, v167, v159
	v_add_f32_e32 v153, v153, v159
	ds_bpermute_b32 v159, v157, v153
	v_cvt_pk_bf16_f32 v160, v160, v161
	v_cvt_pk_bf16_f32 v161, v186, v187
	v_cvt_pk_bf16_f32 v162, v162, v163
	v_cvt_pk_bf16_f32 v163, v172, v173
	s_waitcnt lgkmcnt(0)
	v_add_f32_e32 v153, v153, v159
	ds_bpermute_b32 v159, v158, v153
	global_store_dwordx4 v[170:171], v[160:163], off offset:256
	s_and_saveexec_b64 s[8:9], s[38:39]
	s_cbranch_execz .LBB0_873
	s_lshl_b32 s66, s6, 2
	v_lshlrev_b64 v[154:155], 7, v[154:155]
	s_ashr_i32 s67, s66, 31
	v_lshl_add_u64 v[154:155], s[4:5], 0, v[154:155]
	v_lshl_add_u64 v[154:155], s[66:67], 2, v[154:155]
	s_lshl_b32 s88, s60, 2
	s_waitcnt lgkmcnt(0)
	v_add_f32_e32 v153, v153, v159
	v_lshl_add_u64 v[154:155], v[154:155], 0, s[88:89]
	global_store_dword v[154:155], v153, off
.LBB0_873:
	s_or_b64 exec, exec, s[8:9]
	v_add_u32_e32 v152, 0xb0, v152
	v_ashrrev_i32_e32 v153, 31, v152
	v_lshlrev_b64 v[154:155], 12, v[152:153]
	v_lshl_add_u64 v[154:155], s[80:81], 0, v[154:155]
	v_lshl_add_u64 v[150:151], v[150:151], 1, v[154:155]
	v_mov_b32_e32 v160, v196
	v_mov_b32_e32 v161, v197
	v_mov_b32_e32 v162, v198
	v_mov_b32_e32 v163, v199
	v_lshlrev_b32_e32 v154, 16, v160
	v_and_b32_e32 v155, 0xffff0000, v160
	v_lshlrev_b32_e32 v160, 16, v161
	v_and_b32_e32 v161, 0xffff0000, v161
	v_pk_add_f32 v[172:173], v[28:29], v[160:161]
	v_pk_add_f32 v[154:155], v[26:27], v[154:155]
	v_lshlrev_b32_e32 v170, 16, v162
	v_and_b32_e32 v171, 0xffff0000, v162
	v_lshlrev_b32_e32 v162, 16, v163
	v_and_b32_e32 v163, 0xffff0000, v163
	s_waitcnt lgkmcnt(0)
	v_mul_f32_e32 v159, v155, v155
	v_mul_f32_e32 v160, v173, v173
	v_pk_add_f32 v[184:185], v[20:21], v[162:163]
	v_pk_add_f32 v[162:163], v[18:19], v[170:171]
	v_fmac_f32_e32 v159, v154, v154
	v_fmac_f32_e32 v160, v172, v172
	v_add_f32_e32 v159, v159, v160
	v_mul_f32_e32 v160, v163, v163
	v_fmac_f32_e32 v160, v162, v162
	v_add_f32_e32 v159, v160, v159
	v_mul_f32_e32 v160, v185, v185
	v_fmac_f32_e32 v160, v184, v184
	v_add_f32_e32 v159, v160, v159
	v_cvt_pk_bf16_f32 v160, v154, v155
	v_cvt_pk_bf16_f32 v161, v172, v173
	v_cvt_pk_bf16_f32 v162, v162, v163
	v_cvt_pk_bf16_f32 v163, v184, v185
	global_store_dwordx4 v[150:151], v[160:163], off
	s_nop 1
	v_mov_b32_e32 v160, v214
	v_mov_b32_e32 v161, v215
	v_mov_b32_e32 v162, v216
	v_mov_b32_e32 v163, v217
	v_lshlrev_b32_e32 v154, 16, v160
	v_and_b32_e32 v155, 0xffff0000, v160
	v_lshlrev_b32_e32 v160, 16, v161
	v_and_b32_e32 v161, 0xffff0000, v161
	v_pk_add_f32 v[172:173], v[8:9], v[160:161]
	v_pk_add_f32 v[154:155], v[6:7], v[154:155]
	v_lshlrev_b32_e32 v170, 16, v162
	v_and_b32_e32 v171, 0xffff0000, v162
	v_lshlrev_b32_e32 v162, 16, v163
	v_and_b32_e32 v163, 0xffff0000, v163
	v_mul_f32_e32 v160, v155, v155
	v_mul_f32_e32 v161, v173, v173
	v_pk_add_f32 v[184:185], v[4:5], v[162:163]
	v_pk_add_f32 v[162:163], v[2:3], v[170:171]
	v_fmac_f32_e32 v160, v154, v154
	v_fmac_f32_e32 v161, v172, v172
	v_add_f32_e32 v160, v160, v161
	v_mul_f32_e32 v161, v163, v163
	v_fmac_f32_e32 v161, v162, v162
	v_add_f32_e32 v160, v161, v160
	v_mul_f32_e32 v161, v185, v185
	v_fmac_f32_e32 v161, v184, v184
	v_add_f32_e32 v160, v161, v160
	v_add_f32_e32 v159, v159, v160
	v_cvt_pk_bf16_f32 v160, v154, v155
	v_cvt_pk_bf16_f32 v161, v172, v173
	v_cvt_pk_bf16_f32 v162, v162, v163
	v_cvt_pk_bf16_f32 v163, v184, v185
	global_store_dwordx4 v[150:151], v[160:163], off offset:256
	ds_bpermute_b32 v150, v157, v159
	s_waitcnt lgkmcnt(0)
	v_add_f32_e32 v150, v159, v150
	ds_bpermute_b32 v151, v158, v150
	s_and_saveexec_b64 s[8:9], s[38:39]
	s_cbranch_execz .LBB0_875
	s_waitcnt lgkmcnt(0)
	v_add_f32_e32 v154, v150, v151
	s_lshl_b32 s66, s6, 2
	v_lshlrev_b64 v[150:151], 7, v[152:153]
	s_ashr_i32 s67, s66, 31
	v_lshl_add_u64 v[150:151], s[4:5], 0, v[150:151]
	v_lshl_add_u64 v[150:151], s[66:67], 2, v[150:151]
	s_lshl_b32 s88, s60, 2
	v_lshl_add_u64 v[150:151], v[150:151], 0, s[88:89]
	global_store_dword v[150:151], v154, off
